# phase-3 work queue: first item static (blockIdx), next-item atomic issued at item tail and consumed at loop top via LDS ds ops (no flat / vmcnt(0) on all waves)
# speedup vs baseline: 1.0005x; 1.0005x over previous
.LBB0_620:
	v_writelane_b32 v255, s46, 51
	s_waitcnt vmcnt(0)
	v_and_b32_e32 v0, 63, v224
	v_lshlrev_b32_e32 v0, 2, v0
	v_writelane_b32 v255, s47, 52
	v_mbcnt_lo_u32_b32 v5, -1, 0
	v_readlane_b32 s0, v255, 6
	v_readlane_b32 s1, v255, 7
	v_readlane_b32 s2, v255, 8
	v_readlane_b32 s3, v255, 9
	v_readlane_b32 s4, v255, 10
	v_readlane_b32 s5, v255, 11
	v_readlane_b32 s6, v255, 12
	v_readlane_b32 s7, v255, 13
	v_readlane_b32 s8, v255, 14
	v_readlane_b32 s9, v255, 15
	v_readlane_b32 s10, v255, 16
	v_readlane_b32 s11, v255, 17
	v_readlane_b32 s12, v255, 18
	v_readlane_b32 s13, v255, 19
	v_readlane_b32 s14, v255, 20
	v_readlane_b32 s15, v255, 21
	s_nop 0
	global_load_dword v1, v0, s[10:11]
	s_nop 0
	global_load_dword v3, v0, s[12:13]
	s_nop 0
	global_load_dword v4, v0, s[14:15]
	v_readlane_b32 s0, v255, 22
	v_readlane_b32 s1, v255, 23
	v_mbcnt_hi_u32_b32 v5, -1, v5
	v_and_b32_e32 v6, 64, v5
	v_xor_b32_e32 v7, 32, v5
	v_add_u32_e32 v6, 64, v6
	v_xor_b32_e32 v8, 16, v5
	global_load_dword v0, v0, s[0:1]
	v_cmp_lt_i32_e32 vcc, v7, v6
	v_xor_b32_e32 v9, 8, v5
	v_xor_b32_e32 v10, 4, v5
	v_cndmask_b32_e32 v7, v5, v7, vcc
	v_cmp_lt_i32_e32 vcc, v8, v6
	v_xor_b32_e32 v11, 2, v5
	v_xor_b32_e32 v12, 1, v5
	v_cndmask_b32_e32 v8, v5, v8, vcc
	v_cmp_lt_i32_e32 vcc, v9, v6
	v_lshlrev_b32_e32 v148, 2, v7
	v_lshlrev_b32_e32 v149, 2, v8
	v_cndmask_b32_e32 v9, v5, v9, vcc
	v_cmp_lt_i32_e32 vcc, v10, v6
	v_lshlrev_b32_e32 v8, 2, v9
	s_add_u32 s0, s28, 0x163fc000
	v_cndmask_b32_e32 v10, v5, v10, vcc
	v_cmp_lt_i32_e32 vcc, v11, v6
	v_lshlrev_b32_e32 v9, 2, v10
	s_addc_u32 s1, s29, 0
	v_cndmask_b32_e32 v11, v5, v11, vcc
	v_cmp_lt_i32_e32 vcc, v12, v6
	s_add_u32 s16, s28, 0x8700000
	s_addc_u32 s17, s29, 0
	v_cndmask_b32_e32 v5, v5, v12, vcc
	s_add_u32 s58, s28, 0x15f00000
	s_addc_u32 s59, s29, 0
	s_add_u32 s64, s28, 0x1600000
	s_addc_u32 s65, s29, 0
	s_waitcnt lgkmcnt(0)
	s_add_u32 s74, s28, 0xfb00000
	v_readlane_b32 s2, v255, 24
	v_readlane_b32 s3, v255, 25
	v_readlane_b32 s4, v255, 26
	v_readlane_b32 s5, v255, 27
	v_readlane_b32 s6, v255, 28
	v_readlane_b32 s7, v255, 29
	v_readlane_b32 s8, v255, 30
	v_readlane_b32 s9, v255, 31
	v_readlane_b32 s10, v255, 32
	v_readlane_b32 s11, v255, 33
	v_readlane_b32 s12, v255, 34
	v_readlane_b32 s13, v255, 35
	v_readlane_b32 s14, v255, 36
	v_readlane_b32 s15, v255, 37
	v_writelane_b32 v255, s0, 49
	s_addc_u32 s75, s29, 0
	s_mov_b64 s[40:41], src_shared_base
	v_writelane_b32 v255, s1, 50
	s_add_u32 s0, s28, 0x10d00000
	s_addc_u32 s1, s29, 0
	v_writelane_b32 v255, s0, 53
	s_mov_b64 s[48:49], 0
	s_mov_b64 s[46:47], 0
	v_writelane_b32 v255, s1, 54
	s_add_u32 s0, s28, 0x11500000
	s_addc_u32 s1, s29, 0
	s_add_u32 s44, s28, 0x6700000
	s_addc_u32 s45, s29, 0
	v_writelane_b32 v255, s0, 55
	s_add_u32 s72, s28, 0xfb20000
	v_mov_b32_e32 v2, 0
	s_movk_i32 s20, 0x3a00
	s_mov_b64 s[50:51], 0x800
	s_movk_i32 s21, 0x110
	s_movk_i32 s22, 0x210
	s_movk_i32 s23, 0x48
	s_movk_i32 s24, 0x90
	s_movk_i32 s25, 0x840
	s_mov_b64 s[52:53], 0x80
	s_mov_b32 s26, 0xf149f2ca
	s_mov_b32 s27, 0x3e38aa3b
	s_waitcnt vmcnt(2)
	v_mul_f32_e32 v6, v1, v3
	ds_bpermute_b32 v6, v148, v6
	v_mov_b32_e32 v137, 0x358637bd
	v_mov_b32_e32 v225, 0xffffd000
	v_mov_b32_e32 v254, 0x13f00000
	v_mov_b32_e32 v144, 0x11f00000
	s_waitcnt lgkmcnt(0)
	v_fmac_f32_e32 v6, v1, v3
	v_lshlrev_b32_e32 v3, 2, v11
	v_mov_b32_e32 v145, 0xffffff80
	s_waitcnt vmcnt(0)
	v_mul_f32_e32 v7, v4, v0
	ds_bpermute_b32 v7, v148, v7
	v_mov_b32_e32 v146, 0x900
	v_mov_b32_e32 v147, 0x1200
	v_writelane_b32 v255, s1, 56
	s_addc_u32 s73, s29, 0
	s_waitcnt lgkmcnt(0)
	v_fmac_f32_e32 v7, v4, v0
	ds_bpermute_b32 v0, v149, v6
	ds_bpermute_b32 v1, v149, v7
	v_lshlrev_b32_e32 v4, 2, v5
	s_add_i32 s40, 16, 0x18800
	s_add_i32 s54, 16, 0x1cc00
	s_waitcnt lgkmcnt(1)
	v_add_f32_e32 v0, v6, v0
	s_waitcnt lgkmcnt(0)
	v_add_f32_e32 v1, v7, v1
	ds_bpermute_b32 v5, v8, v0
	ds_bpermute_b32 v6, v8, v1
	s_add_i32 s55, 16, 0x25800
	v_mov_b32_e32 v151, 0x1b00
	s_waitcnt lgkmcnt(1)
	v_add_f32_e32 v0, v0, v5
	s_waitcnt lgkmcnt(0)
	v_add_f32_e32 v1, v1, v6
	ds_bpermute_b32 v5, v9, v0
	ds_bpermute_b32 v6, v9, v1
	s_waitcnt lgkmcnt(1)
	v_add_f32_e32 v0, v0, v5
	s_waitcnt lgkmcnt(0)
	v_add_f32_e32 v1, v1, v6
	ds_bpermute_b32 v5, v3, v0
	ds_bpermute_b32 v3, v3, v1
	s_waitcnt lgkmcnt(1)
	v_add_f32_e32 v0, v0, v5
	s_waitcnt lgkmcnt(0)
	v_add_f32_e32 v1, v1, v3
	ds_bpermute_b32 v3, v4, v0
	ds_bpermute_b32 v4, v4, v1
	s_waitcnt lgkmcnt(1)
	v_add_f32_e32 v0, v0, v3
	s_waitcnt lgkmcnt(0)
	v_add_f32_e32 v1, v1, v4
	v_mul_f32_e32 v0, 0x3fb8aa3b, v0
	v_mul_f32_e32 v1, 0x3fb8aa3b, v1
	v_exp_f32_e32 v0, v0
	v_exp_f32_e32 v1, v1
	s_nop 0
	v_sub_f32_e32 v0, v0, v1
	v_add_f32_e32 v150, 0x3e4ccccd, v0
	v_readlane_b32 s98, v255, 46
	v_readlane_b32 s99, v255, 47
	s_sub_i32 s98, s98, s99
	s_branch .LBB0_624
.LBB0_621:
	s_or_b64 exec, exec, s[8:9]
	v_readlane_b32 s82, v255, 24
	v_readlane_b32 s83, v255, 25
	v_lshlrev_b32_e32 v3, 2, v3
	s_nop 4
	global_load_dwordx4 v[188:191], v3, s[82:83]
	global_load_dwordx4 v[160:163], v3, s[82:83] offset:64
	global_load_dwordx4 v[164:167], v3, s[82:83] offset:128
	global_load_dwordx4 v[168:171], v3, s[82:83] offset:192
	global_load_dwordx4 v[172:175], v3, s[82:83] offset:256
	global_load_dwordx4 v[176:179], v3, s[82:83] offset:320
	global_load_dwordx4 v[180:183], v3, s[82:83] offset:384
	global_load_dwordx4 v[184:187], v3, s[82:83] offset:448
	v_readlane_b32 s99, v255, 0
	s_cmp_eq_u32 s99, 0
	s_cbranch_scc1 .Lmy_p3_hookA
	s_mov_b64 s[100:101], exec
	s_mov_b64 exec, 1
	v_readlane_b32 s99, v255, 49
	v_mov_b32_e32 v251, 1
	s_nop 1
	v_mov_b32_e32 v252, s99
	v_readlane_b32 s99, v255, 50
	s_nop 1
	v_mov_b32_e32 v253, s99
	s_nop 1
	global_atomic_add v251, v[252:253], v251, off sc0
	s_mov_b64 exec, s[100:101]
.Lmy_p3_hookA:
	ds_bpermute_b32 v4, v149, v113
	ds_bpermute_b32 v5, v149, v112
	v_readlane_b32 s80, v255, 22
	s_waitcnt lgkmcnt(1)
	v_add_f32_e32 v4, v113, v4
	ds_bpermute_b32 v6, v148, v4
	s_waitcnt lgkmcnt(1)
	v_add_f32_e32 v5, v112, v5
	ds_bpermute_b32 v7, v148, v5
	v_mov_b32_e32 v115, v2
	s_waitcnt lgkmcnt(1)
	v_add_f32_e32 v4, v4, v6
	v_div_scale_f32 v6, s[6:7], v4, v4, 1.0
	v_rcp_f32_e32 v8, v6
	s_waitcnt lgkmcnt(0)
	v_add_f32_e32 v5, v5, v7
	v_div_scale_f32 v7, vcc, 1.0, v4, 1.0
	v_fma_f32 v11, -v6, v8, 1.0
	v_fmac_f32_e32 v8, v11, v8
	v_div_scale_f32 v9, s[6:7], v5, v5, v150
	v_mul_f32_e32 v11, v7, v8
	v_rcp_f32_e32 v10, v9
	v_fma_f32 v12, -v6, v11, v7
	v_fmac_f32_e32 v11, v12, v8
	v_fma_f32 v6, -v6, v11, v7
	v_div_fmas_f32 v6, v6, v8, v11
	v_div_fixup_f32 v12, v6, v4, 1.0
	v_fma_f32 v4, -v9, v10, 1.0
	v_fmac_f32_e32 v10, v4, v10
	v_div_scale_f32 v4, vcc, v150, v5, v150
	v_mul_f32_e32 v6, v4, v10
	v_fma_f32 v7, -v9, v6, v4
	v_fmac_f32_e32 v6, v7, v10
	v_fma_f32 v4, -v9, v6, v4
	v_div_fmas_f32 v4, v4, v10, v6
	v_div_fixup_f32 v14, v4, v5, v150
	v_pk_mul_f32 v[8:9], v[80:81], v[14:15] op_sel_hi:[1,0]
	v_pk_mul_f32 v[40:41], v[82:83], v[14:15] op_sel_hi:[1,0]
	v_pk_fma_f32 v[36:37], v[96:97], v[12:13], v[8:9] op_sel_hi:[1,0,1] neg_lo:[0,0,1] neg_hi:[0,0,1]
	v_pk_mul_f32 v[4:5], v[88:89], v[14:15] op_sel_hi:[1,0]
	v_pk_mul_f32 v[6:7], v[90:91], v[14:15] op_sel_hi:[1,0]
	v_pk_mul_f32 v[38:39], v[36:37], v[36:37]
	v_pk_fma_f32 v[40:41], v[98:99], v[12:13], v[40:41] op_sel_hi:[1,0,1] neg_lo:[0,0,1] neg_hi:[0,0,1]
	v_pk_mul_f32 v[48:49], v[68:69], v[14:15] op_sel_hi:[1,0]
	v_pk_mul_f32 v[52:53], v[70:71], v[14:15] op_sel_hi:[1,0]
	v_pk_mul_f32 v[56:57], v[56:57], v[14:15] op_sel_hi:[1,0]
	v_pk_mul_f32 v[58:59], v[58:59], v[14:15] op_sel_hi:[1,0]
	v_pk_mul_f32 v[24:25], v[24:25], v[14:15] op_sel_hi:[1,0]
	v_pk_mul_f32 v[26:27], v[26:27], v[14:15] op_sel_hi:[1,0]
	v_pk_mul_f32 v[64:65], v[64:65], v[14:15] op_sel_hi:[1,0]
	v_pk_mul_f32 v[66:67], v[66:67], v[14:15] op_sel_hi:[1,0]
	v_pk_mul_f32 v[44:45], v[44:45], v[14:15] op_sel_hi:[1,0]
	v_pk_mul_f32 v[46:47], v[46:47], v[14:15] op_sel_hi:[1,0]
	v_pk_mul_f32 v[32:33], v[32:33], v[14:15] op_sel_hi:[1,0]
	v_pk_mul_f32 v[14:15], v[34:35], v[14:15] op_sel_hi:[1,0]
	v_pk_fma_f32 v[4:5], v[84:85], v[12:13], v[4:5] op_sel_hi:[1,0,1] neg_lo:[0,0,1] neg_hi:[0,0,1]
	v_pk_fma_f32 v[6:7], v[86:87], v[12:13], v[6:7] op_sel_hi:[1,0,1] neg_lo:[0,0,1] neg_hi:[0,0,1]
	v_pk_mul_f32 v[42:43], v[40:41], v[40:41]
	v_pk_fma_f32 v[48:49], v[92:93], v[12:13], v[48:49] op_sel_hi:[1,0,1] neg_lo:[0,0,1] neg_hi:[0,0,1]
	v_pk_fma_f32 v[52:53], v[94:95], v[12:13], v[52:53] op_sel_hi:[1,0,1] neg_lo:[0,0,1] neg_hi:[0,0,1]
	v_pk_fma_f32 v[56:57], v[76:77], v[12:13], v[56:57] op_sel_hi:[1,0,1] neg_lo:[0,0,1] neg_hi:[0,0,1]
	v_pk_fma_f32 v[58:59], v[78:79], v[12:13], v[58:59] op_sel_hi:[1,0,1] neg_lo:[0,0,1] neg_hi:[0,0,1]
	v_pk_fma_f32 v[24:25], v[72:73], v[12:13], v[24:25] op_sel_hi:[1,0,1] neg_lo:[0,0,1] neg_hi:[0,0,1]
	v_pk_fma_f32 v[26:27], v[74:75], v[12:13], v[26:27] op_sel_hi:[1,0,1] neg_lo:[0,0,1] neg_hi:[0,0,1]
	v_pk_fma_f32 v[60:61], v[60:61], v[12:13], v[64:65] op_sel_hi:[1,0,1] neg_lo:[0,0,1] neg_hi:[0,0,1]
	v_pk_fma_f32 v[62:63], v[62:63], v[12:13], v[66:67] op_sel_hi:[1,0,1] neg_lo:[0,0,1] neg_hi:[0,0,1]
	v_pk_fma_f32 v[28:29], v[28:29], v[12:13], v[44:45] op_sel_hi:[1,0,1] neg_lo:[0,0,1] neg_hi:[0,0,1]
	v_pk_fma_f32 v[30:31], v[30:31], v[12:13], v[46:47] op_sel_hi:[1,0,1] neg_lo:[0,0,1] neg_hi:[0,0,1]
	v_pk_fma_f32 v[20:21], v[20:21], v[12:13], v[32:33] op_sel_hi:[1,0,1] neg_lo:[0,0,1] neg_hi:[0,0,1]
	v_pk_fma_f32 v[12:13], v[22:23], v[12:13], v[14:15] op_sel_hi:[1,0,1] neg_lo:[0,0,1] neg_hi:[0,0,1]
	v_add_f32_e32 v22, v38, v39
	v_add_f32_e32 v22, v42, v22
	v_pk_mul_f32 v[50:51], v[48:49], v[48:49]
	v_add_f32_e32 v22, v43, v22
	v_add_f32_e32 v22, v50, v22
	v_pk_mul_f32 v[54:55], v[52:53], v[52:53]
	v_add_f32_e32 v22, v51, v22
	v_add_f32_e32 v22, v54, v22
	v_pk_mul_f32 v[68:69], v[56:57], v[56:57]
	v_add_f32_e32 v22, v55, v22
	v_add_f32_e32 v22, v68, v22
	v_pk_mul_f32 v[70:71], v[58:59], v[58:59]
	v_add_f32_e32 v22, v69, v22
	v_add_f32_e32 v22, v70, v22
	v_pk_mul_f32 v[72:73], v[24:25], v[24:25]
	v_add_f32_e32 v22, v71, v22
	v_add_f32_e32 v22, v72, v22
	v_pk_mul_f32 v[74:75], v[26:27], v[26:27]
	v_add_f32_e32 v22, v73, v22
	v_add_f32_e32 v22, v74, v22
	v_pk_mul_f32 v[64:65], v[60:61], v[60:61]
	v_add_f32_e32 v22, v75, v22
	v_add_f32_e32 v22, v64, v22
	v_pk_mul_f32 v[66:67], v[62:63], v[62:63]
	v_add_f32_e32 v22, v65, v22
	v_add_f32_e32 v22, v66, v22
	v_pk_mul_f32 v[44:45], v[28:29], v[28:29]
	v_add_f32_e32 v22, v67, v22
	v_add_f32_e32 v22, v44, v22
	v_pk_mul_f32 v[46:47], v[30:31], v[30:31]
	v_add_f32_e32 v22, v45, v22
	v_add_f32_e32 v22, v46, v22
	v_pk_mul_f32 v[32:33], v[20:21], v[20:21]
	v_add_f32_e32 v22, v47, v22
	v_add_f32_e32 v22, v32, v22
	v_pk_mul_f32 v[14:15], v[12:13], v[12:13]
	v_add_f32_e32 v22, v33, v22
	v_add_f32_e32 v14, v14, v22
	v_pk_mul_f32 v[16:17], v[4:5], v[4:5]
	v_add_f32_e32 v14, v15, v14
	v_add_f32_e32 v14, v16, v14
	v_pk_mul_f32 v[18:19], v[6:7], v[6:7]
	v_add_f32_e32 v14, v17, v14
	v_add_f32_e32 v14, v18, v14
	v_add_f32_e32 v14, v19, v14
	ds_bpermute_b32 v15, v149, v14
	s_mov_b32 s6, 0x800000
	v_readlane_b32 s81, v255, 23
	v_readlane_b32 s84, v255, 26
	v_readlane_b32 s85, v255, 27
	s_waitcnt lgkmcnt(0)
	v_add_f32_e32 v16, v14, v15
	ds_bpermute_b32 v17, v148, v16
	v_lshlrev_b64 v[14:15], 12, v[100:101]
	v_lshl_add_u64 v[14:15], s[44:45], 0, v[14:15]
	v_lshl_add_u64 v[0:1], v[0:1], 1, v[14:15]
	v_lshl_add_u64 v[0:1], v[0:1], 0, v[114:115]
	s_waitcnt lgkmcnt(0)
	v_add_f32_e32 v16, v16, v17
	v_fmamk_f32 v16, v16, 0x3c000000, v137
	v_mul_f32_e32 v17, 0x4b800000, v16
	v_cmp_gt_f32_e32 vcc, s6, v16
	v_readlane_b32 s86, v255, 28
	v_readlane_b32 s87, v255, 29
	v_cndmask_b32_e32 v16, v16, v17, vcc
	v_rsq_f32_e32 v16, v16
	v_readlane_b32 s88, v255, 30
	v_readlane_b32 s89, v255, 31
	v_readlane_b32 s90, v255, 32
	v_mul_f32_e32 v14, 0x45800000, v16
	v_cndmask_b32_e32 v14, v16, v14, vcc
	v_mul_f32_e32 v14, 0x3f4ccccd, v14
	v_pk_mul_f32 v[16:17], v[40:41], v[14:15] op_sel_hi:[1,0]
	v_pk_mul_f32 v[18:19], v[36:37], v[14:15] op_sel_hi:[1,0]
	s_waitcnt vmcnt(7)
	v_pk_mul_f32 v[10:11], v[190:191], v[16:17]
	v_pk_mul_f32 v[8:9], v[188:189], v[18:19]
	v_cvt_pk_bf16_f32 v11, v10, v11
	v_cvt_pk_bf16_f32 v10, v8, v9
	global_store_dwordx2 v[0:1], v[10:11], off
	v_pk_mul_f32 v[16:17], v[48:49], v[14:15] op_sel_hi:[1,0]
	v_pk_mul_f32 v[18:19], v[52:53], v[14:15] op_sel_hi:[1,0]
	v_pk_mul_f32 v[12:13], v[12:13], v[14:15] op_sel_hi:[1,0]
	v_pk_mul_f32 v[4:5], v[4:5], v[14:15] op_sel_hi:[1,0]
	v_pk_mul_f32 v[6:7], v[6:7], v[14:15] op_sel_hi:[1,0]
	v_readlane_b32 s91, v255, 33
	v_readlane_b32 s92, v255, 34
	v_readlane_b32 s93, v255, 35
	v_readlane_b32 s94, v255, 36
	v_readlane_b32 s95, v255, 37
	s_waitcnt vmcnt(7)
	v_pk_mul_f32 v[10:11], v[162:163], v[18:19]
	v_pk_mul_f32 v[8:9], v[160:161], v[16:17]
	v_pk_mul_f32 v[16:17], v[56:57], v[14:15] op_sel_hi:[1,0]
	v_cvt_pk_bf16_f32 v8, v8, v9
	v_cvt_pk_bf16_f32 v9, v10, v11
	global_store_dwordx2 v[0:1], v[8:9], off offset:32
	v_pk_mul_f32 v[18:19], v[58:59], v[14:15] op_sel_hi:[1,0]
	s_waitcnt vmcnt(7)
	v_pk_mul_f32 v[8:9], v[164:165], v[16:17]
	v_pk_mul_f32 v[10:11], v[166:167], v[18:19]
	v_cvt_pk_bf16_f32 v8, v8, v9
	v_cvt_pk_bf16_f32 v9, v10, v11
	global_store_dwordx2 v[0:1], v[8:9], off offset:64
	v_pk_mul_f32 v[16:17], v[24:25], v[14:15] op_sel_hi:[1,0]
	v_pk_mul_f32 v[18:19], v[26:27], v[14:15] op_sel_hi:[1,0]
	s_waitcnt vmcnt(7)
	v_pk_mul_f32 v[8:9], v[168:169], v[16:17]
	v_pk_mul_f32 v[10:11], v[170:171], v[18:19]
	v_cvt_pk_bf16_f32 v8, v8, v9
	v_cvt_pk_bf16_f32 v9, v10, v11
	global_store_dwordx2 v[0:1], v[8:9], off offset:96
	v_pk_mul_f32 v[16:17], v[60:61], v[14:15] op_sel_hi:[1,0]
	v_pk_mul_f32 v[18:19], v[62:63], v[14:15] op_sel_hi:[1,0]
	s_waitcnt vmcnt(7)
	v_pk_mul_f32 v[8:9], v[172:173], v[16:17]
	v_pk_mul_f32 v[10:11], v[174:175], v[18:19]
	v_cvt_pk_bf16_f32 v8, v8, v9
	v_cvt_pk_bf16_f32 v9, v10, v11
	global_store_dwordx2 v[0:1], v[8:9], off offset:128
	v_pk_mul_f32 v[16:17], v[28:29], v[14:15] op_sel_hi:[1,0]
	v_pk_mul_f32 v[18:19], v[30:31], v[14:15] op_sel_hi:[1,0]
	s_waitcnt vmcnt(7)
	v_pk_mul_f32 v[8:9], v[176:177], v[16:17]
	v_pk_mul_f32 v[10:11], v[178:179], v[18:19]
	v_cvt_pk_bf16_f32 v8, v8, v9
	v_cvt_pk_bf16_f32 v9, v10, v11
	global_store_dwordx2 v[0:1], v[8:9], off offset:160
	v_pk_mul_f32 v[16:17], v[20:21], v[14:15] op_sel_hi:[1,0]
	s_waitcnt vmcnt(7)
	v_pk_mul_f32 v[10:11], v[182:183], v[12:13]
	v_pk_mul_f32 v[8:9], v[180:181], v[16:17]
	s_nop 0
	v_cvt_pk_bf16_f32 v8, v8, v9
	v_cvt_pk_bf16_f32 v9, v10, v11
	global_store_dwordx2 v[0:1], v[8:9], off offset:192
	s_waitcnt vmcnt(7)
	v_readfirstlane_b32 s98, v251
	v_pk_mul_f32 v[6:7], v[186:187], v[6:7]
	v_pk_mul_f32 v[4:5], v[184:185], v[4:5]
	s_nop 0
	v_cvt_pk_bf16_f32 v4, v4, v5
	v_cvt_pk_bf16_f32 v5, v6, v7
	global_store_dwordx2 v[0:1], v[4:5], off offset:224

.LBB0_624:
	s_barrier
	v_readlane_b32 s2, v255, 0
	s_cmp_eq_u32 s2, 0
	s_cbranch_scc1 .LBB0_628
	v_readlane_b32 s3, v255, 47
	s_add_i32 s3, s98, s3
	s_mov_b32 s98, 0x7fff0000
	v_mov_b32_e32 v0, 0x27f90
	v_mov_b32_e32 v3, s3
	ds_write_b32 v0, v3
.LBB0_628:
	v_mov_b32_e32 v0, 0x27f90
	s_waitcnt lgkmcnt(0)
	s_barrier
	ds_read_b32 v0, v0
	s_movk_i32 s0, 0x340
	s_movk_i32 s1, 0x33f
	s_waitcnt lgkmcnt(0)
	v_cmp_gt_i32_e32 vcc, s0, v0
	v_cmp_lt_i32_e64 s[2:3], s1, v0
	s_and_saveexec_b64 s[56:57], vcc
	s_cbranch_execz .LBB0_623
	v_cmp_gt_i32_e64 s[4:5], 64, v0
	v_cmp_lt_i32_e32 vcc, 63, v0
	s_and_saveexec_b64 s[6:7], vcc
	s_xor_b64 s[6:7], exec, s[6:7]
	s_cbranch_execz .LBB0_635
	s_movk_i32 s0, 0x13f
	v_cmp_lt_u32_e32 vcc, s0, v0
	s_and_saveexec_b64 s[8:9], vcc
	s_xor_b64 s[8:9], exec, s[8:9]
	s_movk_i32 s0, 0x23f
	v_cmp_lt_u32_e64 s[0:1], s0, v0
	v_add_u32_e32 v1, 0xfffffec0, v0
	s_andn2_saveexec_b64 s[8:9], s[8:9]
	v_subrev_u32_e32 v1, 64, v0
	s_or_b64 s[0:1], s[0:1], exec
	s_or_b64 exec, exec, s[8:9]

.LBB0_708:
	s_or_b64 exec, exec, s[16:17]
	v_readlane_b32 s99, v255, 0
	s_cmp_eq_u32 s99, 0
	s_cbranch_scc1 .Lmy_p3_hookB
	s_mov_b64 s[100:101], exec
	s_mov_b64 exec, 1
	v_readlane_b32 s99, v255, 49
	v_mov_b32_e32 v251, 1
	s_nop 1
	v_mov_b32_e32 v252, s99
	v_readlane_b32 s99, v255, 50
	s_nop 1
	v_mov_b32_e32 v253, s99
	s_nop 1
	global_atomic_add v251, v[252:253], v251, off sc0
	s_mov_b64 exec, s[100:101]
.Lmy_p3_hookB:
	s_and_saveexec_b64 s[0:1], s[8:9]
	s_cbranch_execz .LBB0_710
	v_mov_b32_e32 v0, 0x6800000
	v_mov_b32_e32 v1, 0x6000000
	v_readlane_b32 s8, v255, 38
	v_cndmask_b32_e64 v0, v0, v1, s[6:7]
	v_mov_b32_e32 v1, v2
	v_readlane_b32 s14, v255, 44
	v_readlane_b32 s15, v255, 45
	v_ashrrev_i32_e32 v107, 31, v106
	s_waitcnt vmcnt(24)
	v_lshlrev_b64 v[36:37], 16, v[106:107]
	v_lshl_add_u64 v[0:1], s[14:15], 0, v[0:1]
	v_or_b32_e32 v3, s34, v120
	v_lshl_add_u64 v[0:1], v[0:1], 0, v[36:37]
	v_lshl_add_u32 v36, v121, 9, v3
	v_ashrrev_i32_e32 v37, 31, v36
	v_lshl_add_u64 v[38:39], v[36:37], 2, v[0:1]
	global_store_dword v[38:39], v8, off
	global_store_dword v[38:39], v9, off offset:512
	global_store_dword v[38:39], v10, off offset:1024
	global_store_dword v[38:39], v11, off offset:1536
	v_add_u32_e32 v8, 0x800, v36
	v_ashrrev_i32_e32 v9, 31, v8
	v_lshl_add_u64 v[8:9], v[8:9], 2, v[0:1]
	global_store_dword v[8:9], v4, off
	v_add_u32_e32 v8, 0x880, v36
	v_ashrrev_i32_e32 v9, 31, v8
	v_lshl_add_u64 v[8:9], v[8:9], 2, v[0:1]
	v_add_u32_e32 v4, 0x900, v36
	global_store_dword v[8:9], v5, off
	v_ashrrev_i32_e32 v5, 31, v4
	v_lshl_add_u64 v[4:5], v[4:5], 2, v[0:1]
	global_store_dword v[4:5], v6, off
	v_add_u32_e32 v4, 0x980, v36
	v_ashrrev_i32_e32 v5, 31, v4
	v_lshl_add_u64 v[4:5], v[4:5], 2, v[0:1]
	global_store_dword v[4:5], v7, off
	v_add_u32_e32 v4, 0x1000, v36
	v_ashrrev_i32_e32 v5, 31, v4
	v_lshl_add_u64 v[4:5], v[4:5], 2, v[0:1]
	global_store_dword v[4:5], v16, off
	v_add_u32_e32 v4, 0x1080, v36
	v_ashrrev_i32_e32 v5, 31, v4
	v_lshl_add_u64 v[4:5], v[4:5], 2, v[0:1]
	global_store_dword v[4:5], v17, off
	v_add_u32_e32 v4, 0x1100, v36
	v_ashrrev_i32_e32 v5, 31, v4
	v_lshl_add_u64 v[4:5], v[4:5], 2, v[0:1]
	global_store_dword v[4:5], v18, off
	v_add_u32_e32 v4, 0x1180, v36
	v_ashrrev_i32_e32 v5, 31, v4
	v_lshl_add_u64 v[4:5], v[4:5], 2, v[0:1]
	global_store_dword v[4:5], v19, off
	v_add_u32_e32 v4, 0x1800, v36
	v_ashrrev_i32_e32 v5, 31, v4
	v_lshl_add_u64 v[4:5], v[4:5], 2, v[0:1]
	global_store_dword v[4:5], v12, off
	v_add_u32_e32 v4, 0x1880, v36
	v_ashrrev_i32_e32 v5, 31, v4
	v_lshl_add_u64 v[4:5], v[4:5], 2, v[0:1]
	global_store_dword v[4:5], v13, off
	v_add_u32_e32 v4, 0x1900, v36
	v_ashrrev_i32_e32 v5, 31, v4
	v_lshl_add_u64 v[4:5], v[4:5], 2, v[0:1]
	global_store_dword v[4:5], v14, off
	v_add_u32_e32 v4, 0x1980, v36
	v_ashrrev_i32_e32 v5, 31, v4
	v_lshl_add_u64 v[4:5], v[4:5], 2, v[0:1]
	global_store_dword v[4:5], v15, off
	v_add_u32_e32 v4, 0x2000, v36
	v_ashrrev_i32_e32 v5, 31, v4
	v_lshl_add_u64 v[4:5], v[4:5], 2, v[0:1]
	global_store_dword v[4:5], v24, off
	v_add_u32_e32 v4, 0x2080, v36
	v_ashrrev_i32_e32 v5, 31, v4
	v_lshl_add_u64 v[4:5], v[4:5], 2, v[0:1]
	global_store_dword v[4:5], v25, off
	v_add_u32_e32 v4, 0x2100, v36
	v_ashrrev_i32_e32 v5, 31, v4
	v_lshl_add_u64 v[4:5], v[4:5], 2, v[0:1]
	global_store_dword v[4:5], v26, off
	v_add_u32_e32 v4, 0x2180, v36
	v_ashrrev_i32_e32 v5, 31, v4
	v_lshl_add_u64 v[4:5], v[4:5], 2, v[0:1]
	global_store_dword v[4:5], v27, off
	v_add_u32_e32 v4, 0x2800, v36
	v_ashrrev_i32_e32 v5, 31, v4
	v_lshl_add_u64 v[4:5], v[4:5], 2, v[0:1]
	global_store_dword v[4:5], v20, off
	v_add_u32_e32 v4, 0x2880, v36
	v_ashrrev_i32_e32 v5, 31, v4
	v_lshl_add_u64 v[4:5], v[4:5], 2, v[0:1]
	global_store_dword v[4:5], v21, off
	v_add_u32_e32 v4, 0x2900, v36
	v_ashrrev_i32_e32 v5, 31, v4
	v_lshl_add_u64 v[4:5], v[4:5], 2, v[0:1]
	global_store_dword v[4:5], v22, off
	v_add_u32_e32 v4, 0x2980, v36
	v_ashrrev_i32_e32 v5, 31, v4
	v_lshl_add_u64 v[4:5], v[4:5], 2, v[0:1]
	global_store_dword v[4:5], v23, off
	v_add_u32_e32 v4, 0x3000, v36
	v_ashrrev_i32_e32 v5, 31, v4
	v_lshl_add_u64 v[4:5], v[4:5], 2, v[0:1]
	global_store_dword v[4:5], v32, off
	v_add_u32_e32 v4, 0x3080, v36
	v_ashrrev_i32_e32 v5, 31, v4
	v_lshl_add_u64 v[4:5], v[4:5], 2, v[0:1]
	global_store_dword v[4:5], v33, off
	v_add_u32_e32 v4, 0x3100, v36
	v_ashrrev_i32_e32 v5, 31, v4
	v_lshl_add_u64 v[4:5], v[4:5], 2, v[0:1]
	global_store_dword v[4:5], v34, off
	v_add_u32_e32 v4, 0x3180, v36
	v_ashrrev_i32_e32 v5, 31, v4
	v_lshl_add_u64 v[4:5], v[4:5], 2, v[0:1]
	global_store_dword v[4:5], v35, off
	v_add_u32_e32 v4, 0x3800, v36
	v_ashrrev_i32_e32 v5, 31, v4
	v_lshl_add_u64 v[4:5], v[4:5], 2, v[0:1]
	global_store_dword v[4:5], v28, off
	v_add_u32_e32 v4, 0x3880, v36
	v_ashrrev_i32_e32 v5, 31, v4
	v_lshl_add_u64 v[4:5], v[4:5], 2, v[0:1]
	global_store_dword v[4:5], v29, off
	v_add_u32_e32 v4, 0x3900, v36
	v_ashrrev_i32_e32 v5, 31, v4
	v_lshl_add_u64 v[4:5], v[4:5], 2, v[0:1]
	global_store_dword v[4:5], v30, off
	v_add_u32_e32 v4, 0x3980, v36
	v_ashrrev_i32_e32 v5, 31, v4
	v_lshl_add_u64 v[0:1], v[4:5], 2, v[0:1]
	v_readlane_b32 s9, v255, 39
	v_readlane_b32 s10, v255, 40
	v_readlane_b32 s11, v255, 41
	v_readlane_b32 s12, v255, 42
	v_readlane_b32 s13, v255, 43
	global_store_dword v[0:1], v31, off
.LBB0_710:
	s_or_b64 exec, exec, s[0:1]
	v_readlane_b32 s99, v255, 0
	s_cmp_eq_u32 s99, 0
	s_cbranch_scc1 .Lmy_p3_nowait
	s_waitcnt vmcnt(0)
	v_readfirstlane_b32 s98, v251
.Lmy_p3_nowait:
	s_mov_b64 s[64:65], s[80:81]
	s_mov_b64 s[16:17], s[82:83]
